# lever 5: MLA K tile staged by LDS-DMA (global_load_lds_dwordx4, lane-linear 13-chunk rows incl. pad) instead of load-to-VGPR + ds_write; V unchanged
# speedup vs baseline: 1.0080x; 1.0080x over previous
; #define AT_QK_LD0(kb_) do { if constexpr (NEGM) { const LAS unsigned char* kbp_ = Kl + (kb_) * KBUF + r32 * KROWB + hi * 16; AT_KLD2(0); __builtin_amdgcn_sched_barrier(0); } } while (0)
; template <int DQK, int DV, int RH, bool NEGM> ...
;     ...
;     const int NT = nkv / 64;
;     AT_GLOAD(0); AT_LSTORE(0, 0); __syncthreads();
;     int vs_prev = 2, vs_cur = 0, vs_next = 1;
;     if (!grpB) {
;         for (int t = 0; t < NT; ++t) {
;             const int kb = t & 1;
;             if (t + 1 < NT) AT_GLOAD(t + 1);
;             f32x16 p[RH][2];
;             AT_QK_LD0(kb); AT_QK(kb); AT_VLOAD(vs_cur); AT_SOFTMAX(); AT_PV(vs_cur);
;             if (t + 1 < NT) AT_LSTORE(kb ^ 1, vs_next);
.LBB0_881:
	s_or_b64 exec, exec, s[42:43]
	v_pk_add_f32 v[48:49], v[48:49], v[54:55]
	v_pk_add_f32 v[64:65], v[128:129], v[64:65]
	v_pk_add_f32 v[48:49], v[58:59], v[48:49] op_sel_hi:[0,1]
	v_pk_add_f32 v[52:53], v[52:53], v[56:57]
	v_pk_add_f32 v[48:49], v[64:65], v[48:49]
	v_pk_add_f32 v[70:71], v[118:119], v[70:71]
	v_pk_add_f32 v[48:49], v[52:53], v[48:49]
	v_add_u32_e32 v54, v136, v135
	v_pk_add_f32 v[150:151], v[70:71], v[48:49]
	v_add_u32_e32 v48, 0x8c00, v166
	s_waitcnt vmcnt(0)
	ds_write2_b64 v48, v[74:75], v[76:77] offset1:2
	v_mul_lo_u32 v48, v54, 12
	v_sub_u32_e32 v52, v133, v48
	s_lshr_b32 s21, s61, 4
	v_lshlrev_b32_e32 v48, 3, v52
	v_lshlrev_b32_e32 v175, 4, v52
	v_mov_b64_e32 v[52:53], s[40:41]
	s_and_b32 s42, s21, 7
	v_mul_lo_u32 v174, v54, s56
	v_mad_i64_i32 v[54:55], s[40:41], v54, s51, v[52:53]
	v_pk_add_f32 v[50:51], v[50:51], v[62:63]
	v_ashrrev_i32_e32 v49, 31, v48
	v_mad_u64_u32 v[54:55], s[40:41], s42, v163, v[54:55]
	v_pk_add_f32 v[66:67], v[130:131], v[66:67]
	v_pk_add_f32 v[50:51], v[58:59], v[50:51] op_sel_hi:[0,1]
	v_lshl_add_u64 v[48:49], v[48:49], 1, v[54:55]
	v_pk_add_f32 v[56:57], v[116:117], v[68:69]
	v_pk_add_f32 v[50:51], v[66:67], v[50:51]
	v_mov_b32_e32 v154, v48
	v_mad_i64_i32 v[48:49], s[40:41], v59, s51, v[52:53]
	v_pk_add_f32 v[60:61], v[60:61], v[72:73]
	v_pk_add_f32 v[50:51], v[56:57], v[50:51]
	s_lshl_b32 s43, s42, 6
	v_mad_u64_u32 v[48:49], s[40:41], s42, v163, v[48:49]
	v_pk_add_f32 v[152:153], v[60:61], v[50:51]
	v_lshlrev_b32_e32 v50, 3, v112
	s_add_i32 s40, s47, s43
	v_ashrrev_i32_e32 v51, 31, v50
	s_ashr_i32 s41, s40, 31
	v_lshl_add_u64 v[48:49], v[50:51], 1, v[48:49]
	s_lshl_b64 s[40:41], s[40:41], 13
	v_and_b32_e32 v50, 7, v132
	v_mov_b32_e32 v156, v48
	v_lshl_add_u64 v[48:49], v[78:79], 0, s[40:41]
	v_lshlrev_b32_e32 v148, 4, v50
	v_lshl_add_u64 v[48:49], v[48:49], 0, v[148:149]
	v_mul_u32_u24_e32 v173, 0x90, v134
	s_mov_b32 s21, 1
	v_mov_b32_e32 v158, v48
	s_mov_b32 s42, 2
	s_mov_b32 s43, 1
	s_waitcnt lgkmcnt(0)
	s_barrier
	s_mov_b64 s[98:99], s[28:29]
	s_mov_b64 s[100:101], s[30:31]
	v_add_u32_e32 v244, v174, v175
	v_add_u32_e32 v245, v171, v172
	s_mov_b32 s71, 0x13b13b14
	s_mov_b32 s72, 0x15555556
	v_add_u32_e32 v148, s79, v184
	v_mul_hi_u32 v160, v148, s71
	v_mul_u32_u24_e32 v161, 13, v160
	v_sub_u32_e32 v161, v148, v161
	v_min_u32_e32 v161, 11, v161
	v_mul_u32_u24_e32 v160, 0x600, v160
	v_lshl_add_u32 v241, v161, 4, v160
	v_mul_hi_u32 v160, v148, s72
	v_mul_u32_u24_e32 v161, 12, v160
	v_sub_u32_e32 v161, v148, v161
	v_mul_u32_u24_e32 v160, 0x600, v160
	v_lshl_add_u32 v160, v161, 4, v160
	v_sub_u32_e32 v241, v241, v160
	v_add_u32_e32 v241, v241, v154
	v_add_u32_e32 v148, 0x200, v148
	v_mul_hi_u32 v160, v148, s71
	v_mul_u32_u24_e32 v161, 13, v160
	v_sub_u32_e32 v161, v148, v161
	v_min_u32_e32 v161, 11, v161
	v_mul_u32_u24_e32 v160, 0x600, v160
	v_lshl_add_u32 v242, v161, 4, v160
	v_mul_hi_u32 v160, v148, s72
	v_mul_u32_u24_e32 v161, 12, v160
	v_sub_u32_e32 v161, v148, v161
	v_mul_u32_u24_e32 v160, 0x600, v160
	v_lshl_add_u32 v160, v161, 4, v160
	v_sub_u32_e32 v242, v242, v160
	v_add_u32_e32 v242, v242, v156
	s_cmpk_lt_u32 s79, 0x140
	s_cselect_b64 s[68:69], -1, 0
	s_lshl_b32 s70, s79, 4
	s_cmp_eq_u32 s65, 0
	s_cbranch_scc0 .Lmlac_loop

.Lmla_renorm_back:
	ds_read_b128 v[48:51], v169 offset:13312
	ds_read_b128 v[52:55], v169 offset:13344
	ds_read_b128 v[116:119], v169 offset:19968
	ds_read_b128 v[120:123], v169 offset:20000
	s_mov_b32 m0, s70
	s_nop 0
	global_load_lds_dwordx4 v241, s[98:99]
	s_add_i32 m0, s70, 8192
	s_mov_b64 exec, s[68:69]
	global_load_lds_dwordx4 v242, s[98:99]
	s_mov_b64 exec, -1
	global_load_dwordx4 v[112:115], v158, s[100:101]
	s_add_u32 s98, s98, 0x18000
	s_addc_u32 s99, s99, 0
	s_add_u32 s100, s100, 0x80
	s_addc_u32 s101, s101, 0
	s_waitcnt lgkmcnt(3)
	v_mfma_f32_32x32x16_bf16 v[64:79], v[48:51], v[100:103], v[32:47]
	ds_read_b128 v[124:127], v169 offset:13376
	ds_read_b128 v[128:131], v169 offset:13408
	ds_read_b128 v[132:135], v169 offset:20032
	ds_read_b128 v[136:139], v169 offset:20064
	s_waitcnt lgkmcnt(4)
	v_mfma_f32_32x32x16_bf16 v[64:79], v[52:55], v[96:99], v[64:79]
	v_mfma_f32_32x32x16_bf16 v[48:63], v[116:119], v[100:103], v[32:47]
	v_mfma_f32_32x32x16_bf16 v[48:63], v[120:123], v[96:99], v[48:63]
	s_waitcnt lgkmcnt(1)
	v_mfma_f32_32x32x16_bf16 v[64:79], v[124:127], v[92:95], v[64:79]
	v_mfma_f32_32x32x16_bf16 v[48:63], v[132:135], v[92:95], v[48:63]
	v_mfma_f32_32x32x16_bf16 v[64:79], v[128:131], v[88:91], v[64:79]
	ds_read_b128 v[116:119], v169 offset:13440
	ds_read_b128 v[120:123], v169 offset:13472
	ds_read_b128 v[128:131], v169 offset:20096
	ds_read_b128 v[176:179], v169 offset:20128
	s_waitcnt lgkmcnt(3)
	v_mfma_f32_32x32x16_bf16 v[48:63], v[136:139], v[88:91], v[48:63]
	v_mfma_f32_32x32x16_bf16 v[64:79], v[116:119], v[84:87], v[64:79]
	ds_read_b128 v[136:139], v170 offset:35840
	ds_read_b128 v[124:127], v170 offset:35872
	s_waitcnt lgkmcnt(3)
	v_mfma_f32_32x32x16_bf16 v[48:63], v[128:131], v[84:87], v[48:63]
	v_mfma_f32_32x32x16_bf16 v[64:79], v[120:123], v[80:83], v[64:79]
	ds_read_b128 v[132:135], v170 offset:35904
	ds_read_b128 v[120:123], v170 offset:35936
	ds_read_b128 v[144:147], v170 offset:40448
	ds_read_b128 v[140:143], v170 offset:40480
	ds_read_b128 v[128:131], v170 offset:40512
	ds_read_b128 v[116:119], v170 offset:40544
	s_waitcnt lgkmcnt(8)
	v_mfma_f32_32x32x16_bf16 v[48:63], v[176:179], v[80:83], v[48:63]
	s_add_i32 s43, s43, 1
	s_nop 3
	v_exp_f32_e32 v160, v64
	v_exp_f32_e32 v161, v65
	v_exp_f32_e32 v64, v66
	v_exp_f32_e32 v65, v67
	v_exp_f32_e32 v68, v68
	v_exp_f32_e32 v69, v69
	v_exp_f32_e32 v66, v70
	v_exp_f32_e32 v67, v71
	v_cvt_pk_bf16_f32 v176, v160, v161
	v_cvt_pk_bf16_f32 v177, v64, v65
	v_cvt_pk_bf16_f32 v178, v68, v69
	v_cvt_pk_bf16_f32 v179, v66, v67
	v_exp_f32_e32 v70, v74
	v_exp_f32_e32 v71, v75
	s_waitcnt lgkmcnt(0)
	v_mfma_f32_32x32x16_bf16 v[16:31], v[136:139], v[176:179], v[16:31]
	v_exp_f32_e32 v136, v72
	v_exp_f32_e32 v137, v73
	v_exp_f32_e32 v74, v76
	v_exp_f32_e32 v75, v77
	v_exp_f32_e32 v72, v78
	v_exp_f32_e32 v73, v79
	v_exp_f32_e32 v76, v48
	v_mfma_f32_32x32x16_bf16 v[0:15], v[144:147], v[176:179], v[0:15]
	v_cvt_pk_bf16_f32 v144, v136, v137
	v_cvt_pk_bf16_f32 v145, v70, v71
	v_cvt_pk_bf16_f32 v146, v74, v75
	v_cvt_pk_bf16_f32 v147, v72, v73
	v_exp_f32_e32 v77, v49
	v_exp_f32_e32 v48, v50
	v_exp_f32_e32 v49, v51
	v_mfma_f32_32x32x16_bf16 v[16:31], v[124:127], v[144:147], v[16:31]
	v_exp_f32_e32 v52, v52
	v_exp_f32_e32 v53, v53
	v_exp_f32_e32 v50, v54
	v_exp_f32_e32 v51, v55
	v_cvt_pk_bf16_f32 v124, v76, v77
	v_cvt_pk_bf16_f32 v125, v48, v49
	v_cvt_pk_bf16_f32 v126, v52, v53
	v_mfma_f32_32x32x16_bf16 v[0:15], v[140:143], v[144:147], v[0:15]
	v_cvt_pk_bf16_f32 v127, v50, v51
	v_exp_f32_e32 v78, v56
	v_exp_f32_e32 v79, v57
	v_exp_f32_e32 v54, v58
	v_exp_f32_e32 v55, v59
	v_exp_f32_e32 v58, v60
	v_exp_f32_e32 v59, v61
	v_mfma_f32_32x32x16_bf16 v[16:31], v[132:135], v[124:127], v[16:31]
	v_exp_f32_e32 v56, v62
	v_exp_f32_e32 v57, v63
	v_cvt_pk_bf16_f32 v60, v78, v79
	v_cvt_pk_bf16_f32 v61, v54, v55
	v_cvt_pk_bf16_f32 v62, v58, v59
	v_cvt_pk_bf16_f32 v63, v56, v57
	v_mfma_f32_32x32x16_bf16 v[0:15], v[128:131], v[124:127], v[0:15]
	v_mfma_f32_32x32x16_bf16 v[16:31], v[120:123], v[60:63], v[16:31]
	v_mfma_f32_32x32x16_bf16 v[0:15], v[116:119], v[60:63], v[0:15]
	s_waitcnt vmcnt(0)
	ds_write2_b64 v247, v[112:113], v[114:115] offset1:2
	v_pk_add_f32 v[48:49], v[64:65], v[48:49]
	v_pk_add_f32 v[60:61], v[160:161], v[76:77]
	v_pk_add_f32 v[48:49], v[152:153], v[48:49]
	v_pk_add_f32 v[50:51], v[66:67], v[50:51]
	v_pk_add_f32 v[60:61], v[150:151], v[60:61]
	v_pk_add_f32 v[52:53], v[68:69], v[52:53]
	v_pk_add_f32 v[48:49], v[50:51], v[48:49]
	v_pk_add_f32 v[50:51], v[70:71], v[54:55]
	v_pk_add_f32 v[52:53], v[52:53], v[60:61]
	v_pk_add_f32 v[60:61], v[136:137], v[78:79]
	v_pk_add_f32 v[48:49], v[50:51], v[48:49]
	v_pk_add_f32 v[50:51], v[72:73], v[56:57]
	v_pk_add_f32 v[52:53], v[60:61], v[52:53]
	v_pk_add_f32 v[58:59], v[74:75], v[58:59]
	v_pk_add_f32 v[152:153], v[50:51], v[48:49]
	v_pk_add_f32 v[150:151], v[58:59], v[52:53]
	s_waitcnt lgkmcnt(0)
	s_barrier
	ds_read_b128 v[48:51], v169
	ds_read_b128 v[52:55], v169 offset:32
	ds_read_b128 v[116:119], v169 offset:6656
	ds_read_b128 v[120:123], v169 offset:6688
	s_add_i32 m0, s70, 13312
	s_nop 0
	global_load_lds_dwordx4 v241, s[98:99]
	s_add_i32 m0, s70, 21504
	s_mov_b64 exec, s[68:69]
	global_load_lds_dwordx4 v242, s[98:99]
	s_mov_b64 exec, -1
	global_load_dwordx4 v[112:115], v158, s[100:101]
	s_add_u32 s98, s98, 0x18000
	s_addc_u32 s99, s99, 0
	s_add_u32 s100, s100, 0x80
	s_addc_u32 s101, s101, 0
	s_waitcnt lgkmcnt(3)
	v_mfma_f32_32x32x16_bf16 v[64:79], v[48:51], v[100:103], v[32:47]
	ds_read_b128 v[124:127], v169 offset:64
	ds_read_b128 v[128:131], v169 offset:96
	ds_read_b128 v[132:135], v169 offset:6720
	ds_read_b128 v[136:139], v169 offset:6752
	s_waitcnt lgkmcnt(4)
	v_mfma_f32_32x32x16_bf16 v[64:79], v[52:55], v[96:99], v[64:79]
	v_mfma_f32_32x32x16_bf16 v[48:63], v[116:119], v[100:103], v[32:47]
	v_mfma_f32_32x32x16_bf16 v[48:63], v[120:123], v[96:99], v[48:63]
	s_waitcnt lgkmcnt(1)
	v_mfma_f32_32x32x16_bf16 v[64:79], v[124:127], v[92:95], v[64:79]
	v_mfma_f32_32x32x16_bf16 v[48:63], v[132:135], v[92:95], v[48:63]
	v_mfma_f32_32x32x16_bf16 v[64:79], v[128:131], v[88:91], v[64:79]
	ds_read_b128 v[116:119], v169 offset:128
	ds_read_b128 v[120:123], v169 offset:160
	ds_read_b128 v[128:131], v169 offset:6784
	ds_read_b128 v[176:179], v169 offset:6816
	s_waitcnt lgkmcnt(3)
	v_mfma_f32_32x32x16_bf16 v[48:63], v[136:139], v[88:91], v[48:63]
	v_mfma_f32_32x32x16_bf16 v[64:79], v[116:119], v[84:87], v[64:79]
	ds_read_b128 v[136:139], v170 offset:45056
	ds_read_b128 v[124:127], v170 offset:45088
	s_waitcnt lgkmcnt(3)
	v_mfma_f32_32x32x16_bf16 v[48:63], v[128:131], v[84:87], v[48:63]
	v_mfma_f32_32x32x16_bf16 v[64:79], v[120:123], v[80:83], v[64:79]
	ds_read_b128 v[132:135], v170 offset:45120
	ds_read_b128 v[120:123], v170 offset:45152
	ds_read_b128 v[144:147], v170 offset:49664
	ds_read_b128 v[140:143], v170 offset:49696
	ds_read_b128 v[128:131], v170 offset:49728
	ds_read_b128 v[116:119], v170 offset:49760
	s_waitcnt lgkmcnt(8)
	v_mfma_f32_32x32x16_bf16 v[48:63], v[176:179], v[80:83], v[48:63]
	s_add_i32 s43, s43, 1
	s_nop 3
	v_exp_f32_e32 v160, v64
	v_exp_f32_e32 v161, v65
	v_exp_f32_e32 v64, v66
	v_exp_f32_e32 v65, v67
	v_exp_f32_e32 v68, v68
	v_exp_f32_e32 v69, v69
	v_exp_f32_e32 v66, v70
	v_exp_f32_e32 v67, v71
	v_cvt_pk_bf16_f32 v176, v160, v161
	v_cvt_pk_bf16_f32 v177, v64, v65
	v_cvt_pk_bf16_f32 v178, v68, v69
	v_cvt_pk_bf16_f32 v179, v66, v67
	v_exp_f32_e32 v70, v74
	v_exp_f32_e32 v71, v75
	s_waitcnt lgkmcnt(0)
	v_mfma_f32_32x32x16_bf16 v[16:31], v[136:139], v[176:179], v[16:31]
	v_exp_f32_e32 v136, v72
	v_exp_f32_e32 v137, v73
	v_exp_f32_e32 v74, v76
	v_exp_f32_e32 v75, v77
	v_exp_f32_e32 v72, v78
	v_exp_f32_e32 v73, v79
	v_exp_f32_e32 v76, v48
	v_mfma_f32_32x32x16_bf16 v[0:15], v[144:147], v[176:179], v[0:15]
	v_cvt_pk_bf16_f32 v144, v136, v137
	v_cvt_pk_bf16_f32 v145, v70, v71
	v_cvt_pk_bf16_f32 v146, v74, v75
	v_cvt_pk_bf16_f32 v147, v72, v73
	v_exp_f32_e32 v77, v49
	v_exp_f32_e32 v48, v50
	v_exp_f32_e32 v49, v51
	v_mfma_f32_32x32x16_bf16 v[16:31], v[124:127], v[144:147], v[16:31]
	v_exp_f32_e32 v52, v52
	v_exp_f32_e32 v53, v53
	v_exp_f32_e32 v50, v54
	v_exp_f32_e32 v51, v55
	v_cvt_pk_bf16_f32 v124, v76, v77
	v_cvt_pk_bf16_f32 v125, v48, v49
	v_cvt_pk_bf16_f32 v126, v52, v53
	v_mfma_f32_32x32x16_bf16 v[0:15], v[140:143], v[144:147], v[0:15]
	v_cvt_pk_bf16_f32 v127, v50, v51
	v_exp_f32_e32 v78, v56
	v_exp_f32_e32 v79, v57
	v_exp_f32_e32 v54, v58
	v_exp_f32_e32 v55, v59
	v_exp_f32_e32 v58, v60
	v_exp_f32_e32 v59, v61
	v_mfma_f32_32x32x16_bf16 v[16:31], v[132:135], v[124:127], v[16:31]
	v_exp_f32_e32 v56, v62
	v_exp_f32_e32 v57, v63
	v_cvt_pk_bf16_f32 v60, v78, v79
	v_cvt_pk_bf16_f32 v61, v54, v55
	v_cvt_pk_bf16_f32 v62, v58, v59
	v_cvt_pk_bf16_f32 v63, v56, v57
	v_mfma_f32_32x32x16_bf16 v[0:15], v[128:131], v[124:127], v[0:15]
	v_mfma_f32_32x32x16_bf16 v[16:31], v[120:123], v[60:63], v[16:31]
	v_mfma_f32_32x32x16_bf16 v[0:15], v[116:119], v[60:63], v[0:15]
	s_waitcnt vmcnt(0)
	ds_write2_b64 v243, v[112:113], v[114:115] offset1:2
	v_pk_add_f32 v[48:49], v[64:65], v[48:49]
	v_pk_add_f32 v[60:61], v[160:161], v[76:77]
	v_pk_add_f32 v[48:49], v[152:153], v[48:49]
	v_pk_add_f32 v[50:51], v[66:67], v[50:51]
	v_pk_add_f32 v[60:61], v[150:151], v[60:61]
	v_pk_add_f32 v[52:53], v[68:69], v[52:53]
	v_pk_add_f32 v[48:49], v[50:51], v[48:49]
	v_pk_add_f32 v[50:51], v[70:71], v[54:55]
	v_pk_add_f32 v[52:53], v[52:53], v[60:61]
	v_pk_add_f32 v[60:61], v[136:137], v[78:79]
	v_pk_add_f32 v[48:49], v[50:51], v[48:49]
	v_pk_add_f32 v[50:51], v[72:73], v[56:57]
	v_pk_add_f32 v[52:53], v[60:61], v[52:53]
	v_pk_add_f32 v[58:59], v[74:75], v[58:59]
	v_pk_add_f32 v[152:153], v[50:51], v[48:49]
	v_pk_add_f32 v[150:151], v[58:59], v[52:53]
	s_cmp_lg_u32 s43, 63
	s_waitcnt lgkmcnt(0)
	s_barrier
	s_cbranch_scc0 .Lmla_exit
	ds_read_b128 v[48:51], v169 offset:13312
	ds_read_b128 v[52:55], v169 offset:13344
	ds_read_b128 v[116:119], v169 offset:19968
	ds_read_b128 v[120:123], v169 offset:20000
	s_mov_b32 m0, s70
	s_nop 0
	global_load_lds_dwordx4 v241, s[98:99]
	s_add_i32 m0, s70, 8192
	s_mov_b64 exec, s[68:69]
	global_load_lds_dwordx4 v242, s[98:99]
	s_mov_b64 exec, -1
	global_load_dwordx4 v[112:115], v158, s[100:101]
	s_add_u32 s98, s98, 0x18000
	s_addc_u32 s99, s99, 0
	s_add_u32 s100, s100, 0x80
	s_addc_u32 s101, s101, 0
	s_waitcnt lgkmcnt(3)
	v_mfma_f32_32x32x16_bf16 v[64:79], v[48:51], v[100:103], v[32:47]
	ds_read_b128 v[124:127], v169 offset:13376
	ds_read_b128 v[128:131], v169 offset:13408
	ds_read_b128 v[132:135], v169 offset:20032
	ds_read_b128 v[136:139], v169 offset:20064
	s_waitcnt lgkmcnt(4)
	v_mfma_f32_32x32x16_bf16 v[64:79], v[52:55], v[96:99], v[64:79]
	v_mfma_f32_32x32x16_bf16 v[48:63], v[116:119], v[100:103], v[32:47]
	v_mfma_f32_32x32x16_bf16 v[48:63], v[120:123], v[96:99], v[48:63]
	s_waitcnt lgkmcnt(1)
	v_mfma_f32_32x32x16_bf16 v[64:79], v[124:127], v[92:95], v[64:79]
	v_mfma_f32_32x32x16_bf16 v[48:63], v[132:135], v[92:95], v[48:63]
	v_mfma_f32_32x32x16_bf16 v[64:79], v[128:131], v[88:91], v[64:79]
	ds_read_b128 v[116:119], v169 offset:13440
	ds_read_b128 v[120:123], v169 offset:13472
	ds_read_b128 v[128:131], v169 offset:20096
	ds_read_b128 v[176:179], v169 offset:20128
	s_waitcnt lgkmcnt(3)
	v_mfma_f32_32x32x16_bf16 v[48:63], v[136:139], v[88:91], v[48:63]
	v_mfma_f32_32x32x16_bf16 v[64:79], v[116:119], v[84:87], v[64:79]
	ds_read_b128 v[136:139], v170 offset:26624
	ds_read_b128 v[124:127], v170 offset:26656
	s_waitcnt lgkmcnt(3)
	v_mfma_f32_32x32x16_bf16 v[48:63], v[128:131], v[84:87], v[48:63]
	v_mfma_f32_32x32x16_bf16 v[64:79], v[120:123], v[80:83], v[64:79]
	ds_read_b128 v[132:135], v170 offset:26688
	ds_read_b128 v[120:123], v170 offset:26720
	ds_read_b128 v[144:147], v170 offset:31232
	ds_read_b128 v[140:143], v170 offset:31264
	ds_read_b128 v[128:131], v170 offset:31296
	ds_read_b128 v[116:119], v170 offset:31328
	s_waitcnt lgkmcnt(8)
	v_mfma_f32_32x32x16_bf16 v[48:63], v[176:179], v[80:83], v[48:63]
	s_add_i32 s43, s43, 1
	s_nop 3
	v_exp_f32_e32 v160, v64
	v_exp_f32_e32 v161, v65
	v_exp_f32_e32 v64, v66
	v_exp_f32_e32 v65, v67
	v_exp_f32_e32 v68, v68
	v_exp_f32_e32 v69, v69
	v_exp_f32_e32 v66, v70
	v_exp_f32_e32 v67, v71
	v_cvt_pk_bf16_f32 v176, v160, v161
	v_cvt_pk_bf16_f32 v177, v64, v65
	v_cvt_pk_bf16_f32 v178, v68, v69
	v_cvt_pk_bf16_f32 v179, v66, v67
	v_exp_f32_e32 v70, v74
	v_exp_f32_e32 v71, v75
	s_waitcnt lgkmcnt(0)
	v_mfma_f32_32x32x16_bf16 v[16:31], v[136:139], v[176:179], v[16:31]
	v_exp_f32_e32 v136, v72
	v_exp_f32_e32 v137, v73
	v_exp_f32_e32 v74, v76
	v_exp_f32_e32 v75, v77
	v_exp_f32_e32 v72, v78
	v_exp_f32_e32 v73, v79
	v_exp_f32_e32 v76, v48
	v_mfma_f32_32x32x16_bf16 v[0:15], v[144:147], v[176:179], v[0:15]
	v_cvt_pk_bf16_f32 v144, v136, v137
	v_cvt_pk_bf16_f32 v145, v70, v71
	v_cvt_pk_bf16_f32 v146, v74, v75
	v_cvt_pk_bf16_f32 v147, v72, v73
	v_exp_f32_e32 v77, v49
	v_exp_f32_e32 v48, v50
	v_exp_f32_e32 v49, v51
	v_mfma_f32_32x32x16_bf16 v[16:31], v[124:127], v[144:147], v[16:31]
	v_exp_f32_e32 v52, v52
	v_exp_f32_e32 v53, v53
	v_exp_f32_e32 v50, v54
	v_exp_f32_e32 v51, v55
	v_cvt_pk_bf16_f32 v124, v76, v77
	v_cvt_pk_bf16_f32 v125, v48, v49
	v_cvt_pk_bf16_f32 v126, v52, v53
	v_mfma_f32_32x32x16_bf16 v[0:15], v[140:143], v[144:147], v[0:15]
	v_cvt_pk_bf16_f32 v127, v50, v51
	v_exp_f32_e32 v78, v56
	v_exp_f32_e32 v79, v57
	v_exp_f32_e32 v54, v58
	v_exp_f32_e32 v55, v59
	v_exp_f32_e32 v58, v60
	v_exp_f32_e32 v59, v61
	v_mfma_f32_32x32x16_bf16 v[16:31], v[132:135], v[124:127], v[16:31]
	v_exp_f32_e32 v56, v62
	v_exp_f32_e32 v57, v63
	v_cvt_pk_bf16_f32 v60, v78, v79
	v_cvt_pk_bf16_f32 v61, v54, v55
	v_cvt_pk_bf16_f32 v62, v58, v59
	v_cvt_pk_bf16_f32 v63, v56, v57
	v_mfma_f32_32x32x16_bf16 v[0:15], v[128:131], v[124:127], v[0:15]
	v_mfma_f32_32x32x16_bf16 v[16:31], v[120:123], v[60:63], v[16:31]
	v_mfma_f32_32x32x16_bf16 v[0:15], v[116:119], v[60:63], v[0:15]
	s_waitcnt vmcnt(0)
	ds_write2_b64 v246, v[112:113], v[114:115] offset1:2
	v_pk_add_f32 v[48:49], v[64:65], v[48:49]
	v_pk_add_f32 v[60:61], v[160:161], v[76:77]
	v_pk_add_f32 v[48:49], v[152:153], v[48:49]
	v_pk_add_f32 v[50:51], v[66:67], v[50:51]
	v_pk_add_f32 v[60:61], v[150:151], v[60:61]
	v_pk_add_f32 v[52:53], v[68:69], v[52:53]
	v_pk_add_f32 v[48:49], v[50:51], v[48:49]
	v_pk_add_f32 v[50:51], v[70:71], v[54:55]
	v_pk_add_f32 v[52:53], v[52:53], v[60:61]
	v_pk_add_f32 v[60:61], v[136:137], v[78:79]
	v_pk_add_f32 v[48:49], v[50:51], v[48:49]
	v_pk_add_f32 v[50:51], v[72:73], v[56:57]
	v_pk_add_f32 v[52:53], v[60:61], v[52:53]
	v_pk_add_f32 v[58:59], v[74:75], v[58:59]
	v_pk_add_f32 v[152:153], v[50:51], v[48:49]
	v_pk_add_f32 v[150:151], v[58:59], v[52:53]
	s_waitcnt lgkmcnt(0)
	s_barrier
	ds_read_b128 v[48:51], v169
	ds_read_b128 v[52:55], v169 offset:32
	ds_read_b128 v[116:119], v169 offset:6656
	ds_read_b128 v[120:123], v169 offset:6688
	s_add_i32 m0, s70, 13312
	s_nop 0
	global_load_lds_dwordx4 v241, s[98:99]
	s_add_i32 m0, s70, 21504
	s_mov_b64 exec, s[68:69]
	global_load_lds_dwordx4 v242, s[98:99]
	s_mov_b64 exec, -1
	global_load_dwordx4 v[112:115], v158, s[100:101]
	s_add_u32 s98, s98, 0x18000
	s_addc_u32 s99, s99, 0
	s_add_u32 s100, s100, 0x80
	s_addc_u32 s101, s101, 0
	s_waitcnt lgkmcnt(3)
	v_mfma_f32_32x32x16_bf16 v[64:79], v[48:51], v[100:103], v[32:47]
	ds_read_b128 v[124:127], v169 offset:64
	ds_read_b128 v[128:131], v169 offset:96
	ds_read_b128 v[132:135], v169 offset:6720
	ds_read_b128 v[136:139], v169 offset:6752
	s_waitcnt lgkmcnt(4)
	v_mfma_f32_32x32x16_bf16 v[64:79], v[52:55], v[96:99], v[64:79]
	v_mfma_f32_32x32x16_bf16 v[48:63], v[116:119], v[100:103], v[32:47]
	v_mfma_f32_32x32x16_bf16 v[48:63], v[120:123], v[96:99], v[48:63]
	s_waitcnt lgkmcnt(1)
	v_mfma_f32_32x32x16_bf16 v[64:79], v[124:127], v[92:95], v[64:79]
	v_mfma_f32_32x32x16_bf16 v[48:63], v[132:135], v[92:95], v[48:63]
	v_mfma_f32_32x32x16_bf16 v[64:79], v[128:131], v[88:91], v[64:79]
	ds_read_b128 v[116:119], v169 offset:128
	ds_read_b128 v[120:123], v169 offset:160
	ds_read_b128 v[128:131], v169 offset:6784
	ds_read_b128 v[176:179], v169 offset:6816
	s_waitcnt lgkmcnt(3)
	v_mfma_f32_32x32x16_bf16 v[48:63], v[136:139], v[88:91], v[48:63]
	v_mfma_f32_32x32x16_bf16 v[64:79], v[116:119], v[84:87], v[64:79]
	ds_read_b128 v[136:139], v170 offset:35840
	ds_read_b128 v[124:127], v170 offset:35872
	s_waitcnt lgkmcnt(3)
	v_mfma_f32_32x32x16_bf16 v[48:63], v[128:131], v[84:87], v[48:63]
	v_mfma_f32_32x32x16_bf16 v[64:79], v[120:123], v[80:83], v[64:79]
	ds_read_b128 v[132:135], v170 offset:35904
	ds_read_b128 v[120:123], v170 offset:35936
	ds_read_b128 v[144:147], v170 offset:40448
	ds_read_b128 v[140:143], v170 offset:40480
	ds_read_b128 v[128:131], v170 offset:40512
	ds_read_b128 v[116:119], v170 offset:40544
	s_waitcnt lgkmcnt(8)
	v_mfma_f32_32x32x16_bf16 v[48:63], v[176:179], v[80:83], v[48:63]
	s_add_i32 s43, s43, 1
	s_nop 3
	v_exp_f32_e32 v160, v64
	v_exp_f32_e32 v161, v65
	v_exp_f32_e32 v64, v66
	v_exp_f32_e32 v65, v67
	v_exp_f32_e32 v68, v68
	v_exp_f32_e32 v69, v69
	v_exp_f32_e32 v66, v70
	v_exp_f32_e32 v67, v71
	v_cvt_pk_bf16_f32 v176, v160, v161
	v_cvt_pk_bf16_f32 v177, v64, v65
	v_cvt_pk_bf16_f32 v178, v68, v69
	v_cvt_pk_bf16_f32 v179, v66, v67
	v_exp_f32_e32 v70, v74
	v_exp_f32_e32 v71, v75
	s_waitcnt lgkmcnt(0)
	v_mfma_f32_32x32x16_bf16 v[16:31], v[136:139], v[176:179], v[16:31]
	v_exp_f32_e32 v136, v72
	v_exp_f32_e32 v137, v73
	v_exp_f32_e32 v74, v76
	v_exp_f32_e32 v75, v77
	v_exp_f32_e32 v72, v78
	v_exp_f32_e32 v73, v79
	v_exp_f32_e32 v76, v48
	v_mfma_f32_32x32x16_bf16 v[0:15], v[144:147], v[176:179], v[0:15]
	v_cvt_pk_bf16_f32 v144, v136, v137
	v_cvt_pk_bf16_f32 v145, v70, v71
	v_cvt_pk_bf16_f32 v146, v74, v75
	v_cvt_pk_bf16_f32 v147, v72, v73
	v_exp_f32_e32 v77, v49
	v_exp_f32_e32 v48, v50
	v_exp_f32_e32 v49, v51
	v_mfma_f32_32x32x16_bf16 v[16:31], v[124:127], v[144:147], v[16:31]
	v_exp_f32_e32 v52, v52
	v_exp_f32_e32 v53, v53
	v_exp_f32_e32 v50, v54
	v_exp_f32_e32 v51, v55
	v_cvt_pk_bf16_f32 v124, v76, v77
	v_cvt_pk_bf16_f32 v125, v48, v49
	v_cvt_pk_bf16_f32 v126, v52, v53
	v_mfma_f32_32x32x16_bf16 v[0:15], v[140:143], v[144:147], v[0:15]
	v_cvt_pk_bf16_f32 v127, v50, v51
	v_exp_f32_e32 v78, v56
	v_exp_f32_e32 v79, v57
	v_exp_f32_e32 v54, v58
	v_exp_f32_e32 v55, v59
	v_exp_f32_e32 v58, v60
	v_exp_f32_e32 v59, v61
	v_mfma_f32_32x32x16_bf16 v[16:31], v[132:135], v[124:127], v[16:31]
	v_exp_f32_e32 v56, v62
	v_exp_f32_e32 v57, v63
	v_cvt_pk_bf16_f32 v60, v78, v79
	v_cvt_pk_bf16_f32 v61, v54, v55
	v_cvt_pk_bf16_f32 v62, v58, v59
	v_cvt_pk_bf16_f32 v63, v56, v57
	v_mfma_f32_32x32x16_bf16 v[0:15], v[128:131], v[124:127], v[0:15]
	v_mfma_f32_32x32x16_bf16 v[16:31], v[120:123], v[60:63], v[16:31]
	v_mfma_f32_32x32x16_bf16 v[0:15], v[116:119], v[60:63], v[0:15]
	s_waitcnt vmcnt(0)
	ds_write2_b64 v247, v[112:113], v[114:115] offset1:2
	v_pk_add_f32 v[48:49], v[64:65], v[48:49]
	v_pk_add_f32 v[60:61], v[160:161], v[76:77]
	v_pk_add_f32 v[48:49], v[152:153], v[48:49]
	v_pk_add_f32 v[50:51], v[66:67], v[50:51]
	v_pk_add_f32 v[60:61], v[150:151], v[60:61]
	v_pk_add_f32 v[52:53], v[68:69], v[52:53]
	v_pk_add_f32 v[48:49], v[50:51], v[48:49]
	v_pk_add_f32 v[50:51], v[70:71], v[54:55]
	v_pk_add_f32 v[52:53], v[52:53], v[60:61]
	v_pk_add_f32 v[60:61], v[136:137], v[78:79]
	v_pk_add_f32 v[48:49], v[50:51], v[48:49]
	v_pk_add_f32 v[50:51], v[72:73], v[56:57]
	v_pk_add_f32 v[52:53], v[60:61], v[52:53]
	v_pk_add_f32 v[58:59], v[74:75], v[58:59]
	v_pk_add_f32 v[152:153], v[50:51], v[48:49]
	v_pk_add_f32 v[150:151], v[58:59], v[52:53]
	s_waitcnt lgkmcnt(0)
	s_barrier
	ds_read_b128 v[48:51], v169 offset:13312
	ds_read_b128 v[52:55], v169 offset:13344
	ds_read_b128 v[116:119], v169 offset:19968
	ds_read_b128 v[120:123], v169 offset:20000
	s_mov_b32 m0, s70
	s_nop 0
	global_load_lds_dwordx4 v241, s[98:99]
	s_add_i32 m0, s70, 8192
	s_mov_b64 exec, s[68:69]
	global_load_lds_dwordx4 v242, s[98:99]
	s_mov_b64 exec, -1
	global_load_dwordx4 v[112:115], v158, s[100:101]
	s_add_u32 s98, s98, 0x18000
	s_addc_u32 s99, s99, 0
	s_add_u32 s100, s100, 0x80
	s_addc_u32 s101, s101, 0
	s_waitcnt lgkmcnt(3)
	v_mfma_f32_32x32x16_bf16 v[64:79], v[48:51], v[100:103], v[32:47]
	ds_read_b128 v[124:127], v169 offset:13376
	ds_read_b128 v[128:131], v169 offset:13408
	ds_read_b128 v[132:135], v169 offset:20032
	ds_read_b128 v[136:139], v169 offset:20064
	s_waitcnt lgkmcnt(4)
	v_mfma_f32_32x32x16_bf16 v[64:79], v[52:55], v[96:99], v[64:79]
	v_mfma_f32_32x32x16_bf16 v[48:63], v[116:119], v[100:103], v[32:47]
	v_mfma_f32_32x32x16_bf16 v[48:63], v[120:123], v[96:99], v[48:63]
	s_waitcnt lgkmcnt(1)
	v_mfma_f32_32x32x16_bf16 v[64:79], v[124:127], v[92:95], v[64:79]
	v_mfma_f32_32x32x16_bf16 v[48:63], v[132:135], v[92:95], v[48:63]
	v_mfma_f32_32x32x16_bf16 v[64:79], v[128:131], v[88:91], v[64:79]
	ds_read_b128 v[116:119], v169 offset:13440
	ds_read_b128 v[120:123], v169 offset:13472
	ds_read_b128 v[128:131], v169 offset:20096
	ds_read_b128 v[176:179], v169 offset:20128
	s_waitcnt lgkmcnt(3)
	v_mfma_f32_32x32x16_bf16 v[48:63], v[136:139], v[88:91], v[48:63]
	v_mfma_f32_32x32x16_bf16 v[64:79], v[116:119], v[84:87], v[64:79]
	ds_read_b128 v[136:139], v170 offset:45056
	ds_read_b128 v[124:127], v170 offset:45088
	s_waitcnt lgkmcnt(3)
	v_mfma_f32_32x32x16_bf16 v[48:63], v[128:131], v[84:87], v[48:63]
	v_mfma_f32_32x32x16_bf16 v[64:79], v[120:123], v[80:83], v[64:79]
	ds_read_b128 v[132:135], v170 offset:45120
	ds_read_b128 v[120:123], v170 offset:45152
	ds_read_b128 v[144:147], v170 offset:49664
	ds_read_b128 v[140:143], v170 offset:49696
	ds_read_b128 v[128:131], v170 offset:49728
	ds_read_b128 v[116:119], v170 offset:49760
	s_waitcnt lgkmcnt(8)
	v_mfma_f32_32x32x16_bf16 v[48:63], v[176:179], v[80:83], v[48:63]
	s_add_i32 s43, s43, 1
	s_nop 3
	v_exp_f32_e32 v160, v64
	v_exp_f32_e32 v161, v65
	v_exp_f32_e32 v64, v66
	v_exp_f32_e32 v65, v67
	v_exp_f32_e32 v68, v68
	v_exp_f32_e32 v69, v69
	v_exp_f32_e32 v66, v70
	v_exp_f32_e32 v67, v71
	v_cvt_pk_bf16_f32 v176, v160, v161
	v_cvt_pk_bf16_f32 v177, v64, v65
	v_cvt_pk_bf16_f32 v178, v68, v69
	v_cvt_pk_bf16_f32 v179, v66, v67
	v_exp_f32_e32 v70, v74
	v_exp_f32_e32 v71, v75
	s_waitcnt lgkmcnt(0)
	v_mfma_f32_32x32x16_bf16 v[16:31], v[136:139], v[176:179], v[16:31]
	v_exp_f32_e32 v136, v72
	v_exp_f32_e32 v137, v73
	v_exp_f32_e32 v74, v76
	v_exp_f32_e32 v75, v77
	v_exp_f32_e32 v72, v78
	v_exp_f32_e32 v73, v79
	v_exp_f32_e32 v76, v48
	v_mfma_f32_32x32x16_bf16 v[0:15], v[144:147], v[176:179], v[0:15]
	v_cvt_pk_bf16_f32 v144, v136, v137
	v_cvt_pk_bf16_f32 v145, v70, v71
	v_cvt_pk_bf16_f32 v146, v74, v75
	v_cvt_pk_bf16_f32 v147, v72, v73
	v_exp_f32_e32 v77, v49
	v_exp_f32_e32 v48, v50
	v_exp_f32_e32 v49, v51
	v_mfma_f32_32x32x16_bf16 v[16:31], v[124:127], v[144:147], v[16:31]
	v_exp_f32_e32 v52, v52
	v_exp_f32_e32 v53, v53
	v_exp_f32_e32 v50, v54
	v_exp_f32_e32 v51, v55
	v_cvt_pk_bf16_f32 v124, v76, v77
	v_cvt_pk_bf16_f32 v125, v48, v49
	v_cvt_pk_bf16_f32 v126, v52, v53
	v_mfma_f32_32x32x16_bf16 v[0:15], v[140:143], v[144:147], v[0:15]
	v_cvt_pk_bf16_f32 v127, v50, v51
	v_exp_f32_e32 v78, v56
	v_exp_f32_e32 v79, v57
	v_exp_f32_e32 v54, v58
	v_exp_f32_e32 v55, v59
	v_exp_f32_e32 v58, v60
	v_exp_f32_e32 v59, v61
	v_mfma_f32_32x32x16_bf16 v[16:31], v[132:135], v[124:127], v[16:31]
	v_exp_f32_e32 v56, v62
	v_exp_f32_e32 v57, v63
	v_cvt_pk_bf16_f32 v60, v78, v79
	v_cvt_pk_bf16_f32 v61, v54, v55
	v_cvt_pk_bf16_f32 v62, v58, v59
	v_cvt_pk_bf16_f32 v63, v56, v57
	v_mfma_f32_32x32x16_bf16 v[0:15], v[128:131], v[124:127], v[0:15]
	v_mfma_f32_32x32x16_bf16 v[16:31], v[120:123], v[60:63], v[16:31]
	v_mfma_f32_32x32x16_bf16 v[0:15], v[116:119], v[60:63], v[0:15]
	s_waitcnt vmcnt(0)
	ds_write2_b64 v243, v[112:113], v[114:115] offset1:2
	v_pk_add_f32 v[48:49], v[64:65], v[48:49]
	v_pk_add_f32 v[60:61], v[160:161], v[76:77]
	v_pk_add_f32 v[48:49], v[152:153], v[48:49]
	v_pk_add_f32 v[50:51], v[66:67], v[50:51]
	v_pk_add_f32 v[60:61], v[150:151], v[60:61]
	v_pk_add_f32 v[52:53], v[68:69], v[52:53]
	v_pk_add_f32 v[48:49], v[50:51], v[48:49]
	v_pk_add_f32 v[50:51], v[70:71], v[54:55]
	v_pk_add_f32 v[52:53], v[52:53], v[60:61]
	v_pk_add_f32 v[60:61], v[136:137], v[78:79]
	v_pk_add_f32 v[48:49], v[50:51], v[48:49]
	v_pk_add_f32 v[50:51], v[72:73], v[56:57]
	v_pk_add_f32 v[52:53], v[60:61], v[52:53]
	v_pk_add_f32 v[58:59], v[74:75], v[58:59]
	v_pk_add_f32 v[152:153], v[50:51], v[48:49]
	v_pk_add_f32 v[150:151], v[58:59], v[52:53]
	s_waitcnt lgkmcnt(0)
	s_barrier
	ds_read_b128 v[48:51], v169
	ds_read_b128 v[52:55], v169 offset:32
	ds_read_b128 v[116:119], v169 offset:6656
	ds_read_b128 v[120:123], v169 offset:6688
	s_add_i32 m0, s70, 13312
	s_nop 0
	global_load_lds_dwordx4 v241, s[98:99]
	s_add_i32 m0, s70, 21504
	s_mov_b64 exec, s[68:69]
	global_load_lds_dwordx4 v242, s[98:99]
	s_mov_b64 exec, -1
	global_load_dwordx4 v[112:115], v158, s[100:101]
	s_add_u32 s98, s98, 0x18000
	s_addc_u32 s99, s99, 0
	s_add_u32 s100, s100, 0x80
	s_addc_u32 s101, s101, 0
	s_waitcnt lgkmcnt(3)
	v_mfma_f32_32x32x16_bf16 v[64:79], v[48:51], v[100:103], v[32:47]
	ds_read_b128 v[124:127], v169 offset:64
	ds_read_b128 v[128:131], v169 offset:96
	ds_read_b128 v[132:135], v169 offset:6720
	ds_read_b128 v[136:139], v169 offset:6752
	s_waitcnt lgkmcnt(4)
	v_mfma_f32_32x32x16_bf16 v[64:79], v[52:55], v[96:99], v[64:79]
	v_mfma_f32_32x32x16_bf16 v[48:63], v[116:119], v[100:103], v[32:47]
	v_mfma_f32_32x32x16_bf16 v[48:63], v[120:123], v[96:99], v[48:63]
	s_waitcnt lgkmcnt(1)
	v_mfma_f32_32x32x16_bf16 v[64:79], v[124:127], v[92:95], v[64:79]
	v_mfma_f32_32x32x16_bf16 v[48:63], v[132:135], v[92:95], v[48:63]
	v_mfma_f32_32x32x16_bf16 v[64:79], v[128:131], v[88:91], v[64:79]
	ds_read_b128 v[116:119], v169 offset:128
	ds_read_b128 v[120:123], v169 offset:160
	ds_read_b128 v[128:131], v169 offset:6784
	ds_read_b128 v[176:179], v169 offset:6816
	s_waitcnt lgkmcnt(3)
	v_mfma_f32_32x32x16_bf16 v[48:63], v[136:139], v[88:91], v[48:63]
	v_mfma_f32_32x32x16_bf16 v[64:79], v[116:119], v[84:87], v[64:79]
	ds_read_b128 v[136:139], v170 offset:26624
	ds_read_b128 v[124:127], v170 offset:26656
	s_waitcnt lgkmcnt(3)
	v_mfma_f32_32x32x16_bf16 v[48:63], v[128:131], v[84:87], v[48:63]
	v_mfma_f32_32x32x16_bf16 v[64:79], v[120:123], v[80:83], v[64:79]
	ds_read_b128 v[132:135], v170 offset:26688
	ds_read_b128 v[120:123], v170 offset:26720
	ds_read_b128 v[144:147], v170 offset:31232
	ds_read_b128 v[140:143], v170 offset:31264
	ds_read_b128 v[128:131], v170 offset:31296
	ds_read_b128 v[116:119], v170 offset:31328
	s_waitcnt lgkmcnt(8)
	v_mfma_f32_32x32x16_bf16 v[48:63], v[176:179], v[80:83], v[48:63]
	s_add_i32 s43, s43, 1
	s_nop 3
	v_exp_f32_e32 v160, v64
	v_exp_f32_e32 v161, v65
	v_exp_f32_e32 v64, v66
	v_exp_f32_e32 v65, v67
	v_exp_f32_e32 v68, v68
	v_exp_f32_e32 v69, v69
	v_exp_f32_e32 v66, v70
	v_exp_f32_e32 v67, v71
	v_cvt_pk_bf16_f32 v176, v160, v161
	v_cvt_pk_bf16_f32 v177, v64, v65
	v_cvt_pk_bf16_f32 v178, v68, v69
	v_cvt_pk_bf16_f32 v179, v66, v67
	v_exp_f32_e32 v70, v74
	v_exp_f32_e32 v71, v75
	s_waitcnt lgkmcnt(0)
	v_mfma_f32_32x32x16_bf16 v[16:31], v[136:139], v[176:179], v[16:31]
	v_exp_f32_e32 v136, v72
	v_exp_f32_e32 v137, v73
	v_exp_f32_e32 v74, v76
	v_exp_f32_e32 v75, v77
	v_exp_f32_e32 v72, v78
	v_exp_f32_e32 v73, v79
	v_exp_f32_e32 v76, v48
	v_mfma_f32_32x32x16_bf16 v[0:15], v[144:147], v[176:179], v[0:15]
	v_cvt_pk_bf16_f32 v144, v136, v137
	v_cvt_pk_bf16_f32 v145, v70, v71
	v_cvt_pk_bf16_f32 v146, v74, v75
	v_cvt_pk_bf16_f32 v147, v72, v73
	v_exp_f32_e32 v77, v49
	v_exp_f32_e32 v48, v50
	v_exp_f32_e32 v49, v51
	v_mfma_f32_32x32x16_bf16 v[16:31], v[124:127], v[144:147], v[16:31]
	v_exp_f32_e32 v52, v52
	v_exp_f32_e32 v53, v53
	v_exp_f32_e32 v50, v54
	v_exp_f32_e32 v51, v55
	v_cvt_pk_bf16_f32 v124, v76, v77
	v_cvt_pk_bf16_f32 v125, v48, v49
	v_cvt_pk_bf16_f32 v126, v52, v53
	v_mfma_f32_32x32x16_bf16 v[0:15], v[140:143], v[144:147], v[0:15]
	v_cvt_pk_bf16_f32 v127, v50, v51
	v_exp_f32_e32 v78, v56
	v_exp_f32_e32 v79, v57
	v_exp_f32_e32 v54, v58
	v_exp_f32_e32 v55, v59
	v_exp_f32_e32 v58, v60
	v_exp_f32_e32 v59, v61
	v_mfma_f32_32x32x16_bf16 v[16:31], v[132:135], v[124:127], v[16:31]
	v_exp_f32_e32 v56, v62
	v_exp_f32_e32 v57, v63
	v_cvt_pk_bf16_f32 v60, v78, v79
	v_cvt_pk_bf16_f32 v61, v54, v55
	v_cvt_pk_bf16_f32 v62, v58, v59
	v_cvt_pk_bf16_f32 v63, v56, v57
	v_mfma_f32_32x32x16_bf16 v[0:15], v[128:131], v[124:127], v[0:15]
	v_mfma_f32_32x32x16_bf16 v[16:31], v[120:123], v[60:63], v[16:31]
	v_mfma_f32_32x32x16_bf16 v[0:15], v[116:119], v[60:63], v[0:15]
	s_waitcnt vmcnt(0)
	ds_write2_b64 v246, v[112:113], v[114:115] offset1:2
	v_pk_add_f32 v[48:49], v[64:65], v[48:49]
	v_pk_add_f32 v[60:61], v[160:161], v[76:77]
	v_pk_add_f32 v[48:49], v[152:153], v[48:49]
	v_pk_add_f32 v[50:51], v[66:67], v[50:51]
	v_pk_add_f32 v[60:61], v[150:151], v[60:61]
	v_pk_add_f32 v[52:53], v[68:69], v[52:53]
	v_pk_add_f32 v[48:49], v[50:51], v[48:49]
	v_pk_add_f32 v[50:51], v[70:71], v[54:55]
	v_pk_add_f32 v[52:53], v[52:53], v[60:61]
	v_pk_add_f32 v[60:61], v[136:137], v[78:79]
	v_pk_add_f32 v[48:49], v[50:51], v[48:49]
	v_pk_add_f32 v[50:51], v[72:73], v[56:57]
	v_pk_add_f32 v[52:53], v[60:61], v[52:53]
	v_pk_add_f32 v[58:59], v[74:75], v[58:59]
	v_pk_add_f32 v[152:153], v[50:51], v[48:49]
	v_pk_add_f32 v[150:151], v[58:59], v[52:53]
	s_waitcnt lgkmcnt(0)
	s_barrier
	s_branch .Lmla_loop
